# P1 projection epilogue: the eight row rstd reductions batched at the top (2 LDS round trips instead of 16), results kept in v242-v249
# baseline (speedup 1.0000x reference)
.LBB0_114:
	s_ashr_i32 s95, s94, 31
	v_mov_b32_e32 v181, v184
	s_lshl_b64 s[0:1], s[94:95], 14
	s_add_u32 s0, s57, s0
	v_lshlrev_b32_e32 v26, 6, v181
	s_addc_u32 s1, s15, s1
	v_or_b32_e32 v36, v26, v185
	global_load_dwordx4 v[190:193], v36, s[0:1]
	v_mov_b32_e32 v37, v27
	v_lshl_add_u64 v[38:39], s[0:1], 0, v[36:37]
	global_load_dwordx4 v[156:159], v36, s[0:1] offset:1024
	global_load_dwordx4 v[144:147], v36, s[0:1] offset:2048
	global_load_dwordx4 v[124:127], v36, s[0:1] offset:3072
	v_add_co_u32_e32 v36, vcc, s6, v38
	v_and_b32_e32 v182, 64, v224
	s_nop 0
	v_addc_co_u32_e32 v37, vcc, 0, v39, vcc
	global_load_dwordx4 v[104:107], v[36:37], off
	global_load_dwordx4 v[84:87], v[36:37], off offset:1024
	global_load_dwordx4 v[56:59], v[36:37], off offset:2048
	s_nop 0
	global_load_dwordx4 v[36:39], v[36:37], off offset:3072
	v_xor_b32_e32 v180, 16, v224
	v_add_u32_e32 v194, 64, v182
	v_cmp_lt_i32_e32 vcc, v180, v194
	s_cmp_eq_u32 s31, 3
	s_cselect_b64 s[88:89], -1, 0
	v_cndmask_b32_e32 v180, v224, v180, vcc
	v_lshlrev_b32_e32 v189, 2, v180
	s_cmp_lg_u32 s31, 3
	s_waitcnt vmcnt(0)
	v_add_f32_e32 v191, v191, v190
	v_add_f32_e32 v192, v192, v193
	v_add_f32_e32 v157, v157, v156
	v_add_f32_e32 v158, v158, v159
	v_add_f32_e32 v145, v145, v144
	v_add_f32_e32 v146, v146, v147
	v_add_f32_e32 v125, v125, v124
	v_add_f32_e32 v126, v126, v127
	v_add_f32_e32 v105, v105, v104
	v_add_f32_e32 v106, v106, v107
	v_add_f32_e32 v85, v85, v84
	v_add_f32_e32 v86, v86, v87
	v_add_f32_e32 v57, v57, v56
	v_add_f32_e32 v58, v58, v59
	v_add_f32_e32 v37, v37, v36
	v_add_f32_e32 v38, v38, v39
	v_xor_b32_e32 v183, 32, v224
	v_cmp_lt_i32_e32 vcc, v183, v194
	v_add_f32_e32 v242, v191, v192
	v_add_f32_e32 v243, v157, v158
	v_add_f32_e32 v244, v145, v146
	v_add_f32_e32 v245, v125, v126
	v_add_f32_e32 v246, v105, v106
	v_add_f32_e32 v247, v85, v86
	v_add_f32_e32 v248, v57, v58
	v_add_f32_e32 v249, v37, v38
	v_cndmask_b32_e32 v183, v224, v183, vcc
	v_lshlrev_b32_e32 v190, 2, v183
	ds_bpermute_b32 v191, v189, v242
	ds_bpermute_b32 v157, v189, v243
	ds_bpermute_b32 v145, v189, v244
	ds_bpermute_b32 v125, v189, v245
	ds_bpermute_b32 v105, v189, v246
	ds_bpermute_b32 v85, v189, v247
	ds_bpermute_b32 v57, v189, v248
	ds_bpermute_b32 v37, v189, v249
	s_waitcnt lgkmcnt(0)
	v_add_f32_e32 v242, v242, v191
	v_add_f32_e32 v243, v243, v157
	v_add_f32_e32 v244, v244, v145
	v_add_f32_e32 v245, v245, v125
	v_add_f32_e32 v246, v246, v105
	v_add_f32_e32 v247, v247, v85
	v_add_f32_e32 v248, v248, v57
	v_add_f32_e32 v249, v249, v37
	ds_bpermute_b32 v191, v190, v242
	ds_bpermute_b32 v157, v190, v243
	ds_bpermute_b32 v145, v190, v244
	ds_bpermute_b32 v125, v190, v245
	ds_bpermute_b32 v105, v190, v246
	ds_bpermute_b32 v85, v190, v247
	ds_bpermute_b32 v57, v190, v248
	ds_bpermute_b32 v37, v190, v249
	s_waitcnt lgkmcnt(0)
	v_add_f32_e32 v242, v242, v191
	v_add_f32_e32 v243, v243, v157
	v_add_f32_e32 v244, v244, v145
	v_add_f32_e32 v245, v245, v125
	v_add_f32_e32 v246, v246, v105
	v_add_f32_e32 v247, v247, v85
	v_add_f32_e32 v248, v248, v57
	v_add_f32_e32 v249, v249, v37
	v_fmamk_f32 v242, v242, 0x3a800000, v222
	v_fmamk_f32 v243, v243, 0x3a800000, v222
	v_fmamk_f32 v244, v244, 0x3a800000, v222
	v_fmamk_f32 v245, v245, 0x3a800000, v222
	v_fmamk_f32 v246, v246, 0x3a800000, v222
	v_fmamk_f32 v247, v247, 0x3a800000, v222
	v_fmamk_f32 v248, v248, 0x3a800000, v222
	v_fmamk_f32 v249, v249, 0x3a800000, v222
	v_rsq_f32_e32 v242, v242
	v_rsq_f32_e32 v243, v243
	v_rsq_f32_e32 v244, v244
	v_rsq_f32_e32 v245, v245
	v_rsq_f32_e32 v246, v246
	v_rsq_f32_e32 v247, v247
	v_rsq_f32_e32 v248, v248
	v_rsq_f32_e32 v249, v249
	v_mov_b32_e32 v180, v242
	v_pk_mul_f32 v[150:151], v[150:151], v[180:181] op_sel_hi:[1,0]
	v_pk_mul_f32 v[148:149], v[148:149], v[180:181] op_sel_hi:[1,0]
	v_pk_mul_f32 v[154:155], v[154:155], v[180:181] op_sel_hi:[1,0]
	v_pk_mul_f32 v[182:183], v[152:153], v[180:181] op_sel_hi:[1,0]
	s_cbranch_scc1 .LBB0_116
	v_pk_mul_f32 v[152:153], v[150:151], v[150:151]
	v_pk_mul_f32 v[192:193], v[148:149], v[148:149]
	v_mov_b64_e32 v[194:195], s[42:43]
	v_pk_mul_f32 v[196:197], v[154:155], v[154:155]
	v_pk_mul_f32 v[198:199], v[182:183], v[182:183]
	v_pk_fma_f32 v[192:193], v[192:193], s[18:19], v[194:195] op_sel_hi:[1,0,0] neg_lo:[1,0,0] neg_hi:[1,0,0]
	v_pk_fma_f32 v[198:199], v[198:199], s[18:19], v[194:195] op_sel_hi:[1,0,0] neg_lo:[1,0,0] neg_hi:[1,0,0]
	v_pk_fma_f32 v[152:153], v[152:153], s[18:19], v[194:195] op_sel_hi:[1,0,0] neg_lo:[1,0,0] neg_hi:[1,0,0]
	v_pk_fma_f32 v[194:195], v[196:197], s[18:19], v[194:195] op_sel_hi:[1,0,0] neg_lo:[1,0,0] neg_hi:[1,0,0]
	v_pk_mul_f32 v[192:193], v[148:149], v[192:193]
	v_pk_mul_f32 v[198:199], v[182:183], v[198:199]
	v_pk_mul_f32 v[152:153], v[150:151], v[152:153]
	v_pk_mul_f32 v[194:195], v[154:155], v[194:195]
	v_exp_f32_e32 v192, v192
	v_exp_f32_e32 v193, v193
	v_exp_f32_e32 v198, v198
	v_exp_f32_e32 v199, v199
	v_exp_f32_e32 v152, v152
	v_exp_f32_e32 v153, v153
	v_exp_f32_e32 v194, v194
	v_exp_f32_e32 v195, v195
	v_pk_add_f32 v[192:193], v[192:193], 1.0 op_sel_hi:[1,0]
	v_pk_add_f32 v[198:199], v[198:199], 1.0 op_sel_hi:[1,0]
	v_pk_add_f32 v[152:153], v[152:153], 1.0 op_sel_hi:[1,0]
	v_pk_add_f32 v[194:195], v[194:195], 1.0 op_sel_hi:[1,0]
	v_rcp_f32_e32 v192, v192
	v_rcp_f32_e32 v193, v193
	v_rcp_f32_e32 v198, v198
	v_rcp_f32_e32 v199, v199
	v_rcp_f32_e32 v152, v152
	v_rcp_f32_e32 v153, v153
	v_rcp_f32_e32 v194, v194
	v_rcp_f32_e32 v195, v195
	v_pk_mul_f32 v[148:149], v[148:149], v[192:193]
	v_pk_mul_f32 v[150:151], v[150:151], v[152:153]
	v_pk_mul_f32 v[182:183], v[182:183], v[198:199]
	v_pk_mul_f32 v[154:155], v[154:155], v[194:195]

.LBB0_124:
	s_nop 0
	s_and_b64 vcc, exec, s[0:1]
	s_waitcnt lgkmcnt(0)
	v_mov_b32_e32 v136, v243
	v_pk_mul_f32 v[138:139], v[130:131], v[136:137] op_sel_hi:[1,0]
	v_pk_mul_f32 v[128:129], v[128:129], v[136:137] op_sel_hi:[1,0]
	v_pk_mul_f32 v[134:135], v[134:135], v[136:137] op_sel_hi:[1,0]
	v_pk_mul_f32 v[130:131], v[132:133], v[136:137] op_sel_hi:[1,0]
	s_cbranch_vccnz .LBB0_126
	v_pk_mul_f32 v[132:133], v[138:139], v[138:139]
	v_pk_mul_f32 v[142:143], v[128:129], v[128:129]
	v_mov_b64_e32 v[148:149], s[42:43]
	v_pk_mul_f32 v[150:151], v[134:135], v[134:135]
	v_pk_mul_f32 v[152:153], v[130:131], v[130:131]
	v_pk_fma_f32 v[142:143], v[142:143], s[18:19], v[148:149] op_sel_hi:[1,0,0] neg_lo:[1,0,0] neg_hi:[1,0,0]
	v_pk_fma_f32 v[152:153], v[152:153], s[18:19], v[148:149] op_sel_hi:[1,0,0] neg_lo:[1,0,0] neg_hi:[1,0,0]
	v_pk_fma_f32 v[132:133], v[132:133], s[18:19], v[148:149] op_sel_hi:[1,0,0] neg_lo:[1,0,0] neg_hi:[1,0,0]
	v_pk_fma_f32 v[148:149], v[150:151], s[18:19], v[148:149] op_sel_hi:[1,0,0] neg_lo:[1,0,0] neg_hi:[1,0,0]
	v_pk_mul_f32 v[142:143], v[128:129], v[142:143]
	v_pk_mul_f32 v[152:153], v[130:131], v[152:153]
	v_pk_mul_f32 v[132:133], v[138:139], v[132:133]
	v_pk_mul_f32 v[148:149], v[134:135], v[148:149]
	v_exp_f32_e32 v142, v142
	v_exp_f32_e32 v143, v143
	v_exp_f32_e32 v152, v152
	v_exp_f32_e32 v153, v153
	v_exp_f32_e32 v132, v132
	v_exp_f32_e32 v133, v133
	v_exp_f32_e32 v148, v148
	v_exp_f32_e32 v149, v149
	v_pk_add_f32 v[142:143], v[142:143], 1.0 op_sel_hi:[1,0]
	v_pk_add_f32 v[152:153], v[152:153], 1.0 op_sel_hi:[1,0]
	v_pk_add_f32 v[132:133], v[132:133], 1.0 op_sel_hi:[1,0]
	v_pk_add_f32 v[148:149], v[148:149], 1.0 op_sel_hi:[1,0]
	v_rcp_f32_e32 v142, v142
	v_rcp_f32_e32 v143, v143
	v_rcp_f32_e32 v152, v152
	v_rcp_f32_e32 v153, v153
	v_rcp_f32_e32 v132, v132
	v_rcp_f32_e32 v133, v133
	v_rcp_f32_e32 v148, v148
	v_rcp_f32_e32 v149, v149
	v_pk_mul_f32 v[128:129], v[128:129], v[142:143]
	v_pk_mul_f32 v[138:139], v[138:139], v[132:133]
	v_pk_mul_f32 v[130:131], v[130:131], v[152:153]
	v_pk_mul_f32 v[134:135], v[134:135], v[148:149]

.LBB0_134:
	s_nop 0
	s_and_b64 vcc, exec, s[0:1]
	s_waitcnt lgkmcnt(0)
	v_mov_b32_e32 v116, v244
	v_pk_mul_f32 v[118:119], v[110:111], v[116:117] op_sel_hi:[1,0]
	v_pk_mul_f32 v[108:109], v[108:109], v[116:117] op_sel_hi:[1,0]
	v_pk_mul_f32 v[114:115], v[114:115], v[116:117] op_sel_hi:[1,0]
	v_pk_mul_f32 v[110:111], v[112:113], v[116:117] op_sel_hi:[1,0]
	s_cbranch_vccnz .LBB0_136
	v_pk_mul_f32 v[112:113], v[118:119], v[118:119]
	v_pk_mul_f32 v[120:121], v[108:109], v[108:109]
	v_mov_b64_e32 v[122:123], s[42:43]
	v_pk_mul_f32 v[128:129], v[114:115], v[114:115]
	v_pk_mul_f32 v[130:131], v[110:111], v[110:111]
	v_pk_fma_f32 v[120:121], v[120:121], s[18:19], v[122:123] op_sel_hi:[1,0,0] neg_lo:[1,0,0] neg_hi:[1,0,0]
	v_pk_fma_f32 v[130:131], v[130:131], s[18:19], v[122:123] op_sel_hi:[1,0,0] neg_lo:[1,0,0] neg_hi:[1,0,0]
	v_pk_fma_f32 v[112:113], v[112:113], s[18:19], v[122:123] op_sel_hi:[1,0,0] neg_lo:[1,0,0] neg_hi:[1,0,0]
	v_pk_fma_f32 v[122:123], v[128:129], s[18:19], v[122:123] op_sel_hi:[1,0,0] neg_lo:[1,0,0] neg_hi:[1,0,0]
	v_pk_mul_f32 v[120:121], v[108:109], v[120:121]
	v_pk_mul_f32 v[130:131], v[110:111], v[130:131]
	v_pk_mul_f32 v[112:113], v[118:119], v[112:113]
	v_pk_mul_f32 v[122:123], v[114:115], v[122:123]
	v_exp_f32_e32 v120, v120
	v_exp_f32_e32 v121, v121
	v_exp_f32_e32 v130, v130
	v_exp_f32_e32 v131, v131
	v_exp_f32_e32 v112, v112
	v_exp_f32_e32 v113, v113
	v_exp_f32_e32 v122, v122
	v_exp_f32_e32 v123, v123
	v_pk_add_f32 v[120:121], v[120:121], 1.0 op_sel_hi:[1,0]
	v_pk_add_f32 v[130:131], v[130:131], 1.0 op_sel_hi:[1,0]
	v_pk_add_f32 v[112:113], v[112:113], 1.0 op_sel_hi:[1,0]
	v_pk_add_f32 v[122:123], v[122:123], 1.0 op_sel_hi:[1,0]
	v_rcp_f32_e32 v120, v120
	v_rcp_f32_e32 v121, v121
	v_rcp_f32_e32 v130, v130
	v_rcp_f32_e32 v131, v131
	v_rcp_f32_e32 v112, v112
	v_rcp_f32_e32 v113, v113
	v_rcp_f32_e32 v122, v122
	v_rcp_f32_e32 v123, v123
	v_pk_mul_f32 v[108:109], v[108:109], v[120:121]
	v_pk_mul_f32 v[118:119], v[118:119], v[112:113]
	v_pk_mul_f32 v[110:111], v[110:111], v[130:131]
	v_pk_mul_f32 v[114:115], v[114:115], v[122:123]

.LBB0_144:
	s_nop 0
	s_and_b64 vcc, exec, s[0:1]
	s_waitcnt lgkmcnt(0)
	v_mov_b32_e32 v96, v245
	v_pk_mul_f32 v[98:99], v[90:91], v[96:97] op_sel_hi:[1,0]
	v_pk_mul_f32 v[88:89], v[88:89], v[96:97] op_sel_hi:[1,0]
	v_pk_mul_f32 v[94:95], v[94:95], v[96:97] op_sel_hi:[1,0]
	v_pk_mul_f32 v[90:91], v[92:93], v[96:97] op_sel_hi:[1,0]
	s_cbranch_vccnz .LBB0_146
	v_pk_mul_f32 v[92:93], v[98:99], v[98:99]
	v_pk_mul_f32 v[100:101], v[88:89], v[88:89]
	v_mov_b64_e32 v[102:103], s[42:43]
	v_pk_mul_f32 v[108:109], v[94:95], v[94:95]
	v_pk_mul_f32 v[110:111], v[90:91], v[90:91]
	v_pk_fma_f32 v[100:101], v[100:101], s[18:19], v[102:103] op_sel_hi:[1,0,0] neg_lo:[1,0,0] neg_hi:[1,0,0]
	v_pk_fma_f32 v[110:111], v[110:111], s[18:19], v[102:103] op_sel_hi:[1,0,0] neg_lo:[1,0,0] neg_hi:[1,0,0]
	v_pk_fma_f32 v[92:93], v[92:93], s[18:19], v[102:103] op_sel_hi:[1,0,0] neg_lo:[1,0,0] neg_hi:[1,0,0]
	v_pk_fma_f32 v[102:103], v[108:109], s[18:19], v[102:103] op_sel_hi:[1,0,0] neg_lo:[1,0,0] neg_hi:[1,0,0]
	v_pk_mul_f32 v[100:101], v[88:89], v[100:101]
	v_pk_mul_f32 v[110:111], v[90:91], v[110:111]
	v_pk_mul_f32 v[92:93], v[98:99], v[92:93]
	v_pk_mul_f32 v[102:103], v[94:95], v[102:103]
	v_exp_f32_e32 v100, v100
	v_exp_f32_e32 v101, v101
	v_exp_f32_e32 v110, v110
	v_exp_f32_e32 v111, v111
	v_exp_f32_e32 v92, v92
	v_exp_f32_e32 v93, v93
	v_exp_f32_e32 v102, v102
	v_exp_f32_e32 v103, v103
	v_pk_add_f32 v[100:101], v[100:101], 1.0 op_sel_hi:[1,0]
	v_pk_add_f32 v[110:111], v[110:111], 1.0 op_sel_hi:[1,0]
	v_pk_add_f32 v[92:93], v[92:93], 1.0 op_sel_hi:[1,0]
	v_pk_add_f32 v[102:103], v[102:103], 1.0 op_sel_hi:[1,0]
	v_rcp_f32_e32 v100, v100
	v_rcp_f32_e32 v101, v101
	v_rcp_f32_e32 v110, v110
	v_rcp_f32_e32 v111, v111
	v_rcp_f32_e32 v92, v92
	v_rcp_f32_e32 v93, v93
	v_rcp_f32_e32 v102, v102
	v_rcp_f32_e32 v103, v103
	v_pk_mul_f32 v[88:89], v[88:89], v[100:101]
	v_pk_mul_f32 v[98:99], v[98:99], v[92:93]
	v_pk_mul_f32 v[90:91], v[90:91], v[110:111]
	v_pk_mul_f32 v[94:95], v[94:95], v[102:103]

.LBB0_154:
	s_nop 0
	s_and_b64 vcc, exec, s[0:1]
	s_waitcnt lgkmcnt(0)
	v_mov_b32_e32 v76, v246
	v_pk_mul_f32 v[78:79], v[70:71], v[76:77] op_sel_hi:[1,0]
	v_pk_mul_f32 v[68:69], v[68:69], v[76:77] op_sel_hi:[1,0]
	v_pk_mul_f32 v[74:75], v[74:75], v[76:77] op_sel_hi:[1,0]
	v_pk_mul_f32 v[70:71], v[72:73], v[76:77] op_sel_hi:[1,0]
	s_cbranch_vccnz .LBB0_156
	v_pk_mul_f32 v[72:73], v[78:79], v[78:79]
	v_pk_mul_f32 v[80:81], v[68:69], v[68:69]
	v_mov_b64_e32 v[82:83], s[42:43]
	v_pk_mul_f32 v[88:89], v[74:75], v[74:75]
	v_pk_mul_f32 v[90:91], v[70:71], v[70:71]
	v_pk_fma_f32 v[80:81], v[80:81], s[18:19], v[82:83] op_sel_hi:[1,0,0] neg_lo:[1,0,0] neg_hi:[1,0,0]
	v_pk_fma_f32 v[90:91], v[90:91], s[18:19], v[82:83] op_sel_hi:[1,0,0] neg_lo:[1,0,0] neg_hi:[1,0,0]
	v_pk_fma_f32 v[72:73], v[72:73], s[18:19], v[82:83] op_sel_hi:[1,0,0] neg_lo:[1,0,0] neg_hi:[1,0,0]
	v_pk_fma_f32 v[82:83], v[88:89], s[18:19], v[82:83] op_sel_hi:[1,0,0] neg_lo:[1,0,0] neg_hi:[1,0,0]
	v_pk_mul_f32 v[80:81], v[68:69], v[80:81]
	v_pk_mul_f32 v[90:91], v[70:71], v[90:91]
	v_pk_mul_f32 v[72:73], v[78:79], v[72:73]
	v_pk_mul_f32 v[82:83], v[74:75], v[82:83]
	v_exp_f32_e32 v80, v80
	v_exp_f32_e32 v81, v81
	v_exp_f32_e32 v90, v90
	v_exp_f32_e32 v91, v91
	v_exp_f32_e32 v72, v72
	v_exp_f32_e32 v73, v73
	v_exp_f32_e32 v82, v82
	v_exp_f32_e32 v83, v83
	v_pk_add_f32 v[80:81], v[80:81], 1.0 op_sel_hi:[1,0]
	v_pk_add_f32 v[90:91], v[90:91], 1.0 op_sel_hi:[1,0]
	v_pk_add_f32 v[72:73], v[72:73], 1.0 op_sel_hi:[1,0]
	v_pk_add_f32 v[82:83], v[82:83], 1.0 op_sel_hi:[1,0]
	v_rcp_f32_e32 v80, v80
	v_rcp_f32_e32 v81, v81
	v_rcp_f32_e32 v90, v90
	v_rcp_f32_e32 v91, v91
	v_rcp_f32_e32 v72, v72
	v_rcp_f32_e32 v73, v73
	v_rcp_f32_e32 v82, v82
	v_rcp_f32_e32 v83, v83
	v_pk_mul_f32 v[68:69], v[68:69], v[80:81]
	v_pk_mul_f32 v[78:79], v[78:79], v[72:73]
	v_pk_mul_f32 v[70:71], v[70:71], v[90:91]
	v_pk_mul_f32 v[74:75], v[74:75], v[82:83]

.LBB0_164:
	s_nop 0
	s_and_b64 vcc, exec, s[0:1]
	s_waitcnt lgkmcnt(0)
	v_mov_b32_e32 v60, v247
	v_pk_mul_f32 v[62:63], v[50:51], v[60:61] op_sel_hi:[1,0]
	v_pk_mul_f32 v[48:49], v[48:49], v[60:61] op_sel_hi:[1,0]
	v_pk_mul_f32 v[54:55], v[54:55], v[60:61] op_sel_hi:[1,0]
	v_pk_mul_f32 v[50:51], v[52:53], v[60:61] op_sel_hi:[1,0]
	s_cbranch_vccnz .LBB0_166
	v_pk_mul_f32 v[52:53], v[62:63], v[62:63]
	v_pk_mul_f32 v[64:65], v[48:49], v[48:49]
	v_mov_b64_e32 v[66:67], s[42:43]
	v_pk_mul_f32 v[68:69], v[54:55], v[54:55]
	v_pk_mul_f32 v[70:71], v[50:51], v[50:51]
	v_pk_fma_f32 v[64:65], v[64:65], s[18:19], v[66:67] op_sel_hi:[1,0,0] neg_lo:[1,0,0] neg_hi:[1,0,0]
	v_pk_fma_f32 v[70:71], v[70:71], s[18:19], v[66:67] op_sel_hi:[1,0,0] neg_lo:[1,0,0] neg_hi:[1,0,0]
	v_pk_fma_f32 v[52:53], v[52:53], s[18:19], v[66:67] op_sel_hi:[1,0,0] neg_lo:[1,0,0] neg_hi:[1,0,0]
	v_pk_fma_f32 v[66:67], v[68:69], s[18:19], v[66:67] op_sel_hi:[1,0,0] neg_lo:[1,0,0] neg_hi:[1,0,0]
	v_pk_mul_f32 v[64:65], v[48:49], v[64:65]
	v_pk_mul_f32 v[70:71], v[50:51], v[70:71]
	v_pk_mul_f32 v[52:53], v[62:63], v[52:53]
	v_pk_mul_f32 v[66:67], v[54:55], v[66:67]
	v_exp_f32_e32 v64, v64
	v_exp_f32_e32 v65, v65
	v_exp_f32_e32 v70, v70
	v_exp_f32_e32 v71, v71
	v_exp_f32_e32 v52, v52
	v_exp_f32_e32 v53, v53
	v_exp_f32_e32 v66, v66
	v_exp_f32_e32 v67, v67
	v_pk_add_f32 v[64:65], v[64:65], 1.0 op_sel_hi:[1,0]
	v_pk_add_f32 v[70:71], v[70:71], 1.0 op_sel_hi:[1,0]
	v_pk_add_f32 v[52:53], v[52:53], 1.0 op_sel_hi:[1,0]
	v_pk_add_f32 v[66:67], v[66:67], 1.0 op_sel_hi:[1,0]
	v_rcp_f32_e32 v64, v64
	v_rcp_f32_e32 v65, v65
	v_rcp_f32_e32 v70, v70
	v_rcp_f32_e32 v71, v71
	v_rcp_f32_e32 v52, v52
	v_rcp_f32_e32 v53, v53
	v_rcp_f32_e32 v66, v66
	v_rcp_f32_e32 v67, v67
	v_pk_mul_f32 v[48:49], v[48:49], v[64:65]
	v_pk_mul_f32 v[62:63], v[62:63], v[52:53]
	v_pk_mul_f32 v[50:51], v[50:51], v[70:71]
	v_pk_mul_f32 v[54:55], v[54:55], v[66:67]

.LBB0_174:
	s_nop 0
	s_and_b64 vcc, exec, s[0:1]
	s_waitcnt lgkmcnt(0)
	v_mov_b32_e32 v40, v248
	v_pk_mul_f32 v[42:43], v[30:31], v[40:41] op_sel_hi:[1,0]
	v_pk_mul_f32 v[28:29], v[28:29], v[40:41] op_sel_hi:[1,0]
	v_pk_mul_f32 v[34:35], v[34:35], v[40:41] op_sel_hi:[1,0]
	v_pk_mul_f32 v[30:31], v[32:33], v[40:41] op_sel_hi:[1,0]
	s_cbranch_vccnz .LBB0_176
	v_pk_mul_f32 v[32:33], v[42:43], v[42:43]
	v_pk_mul_f32 v[44:45], v[28:29], v[28:29]
	v_mov_b64_e32 v[46:47], s[42:43]
	v_pk_mul_f32 v[48:49], v[34:35], v[34:35]
	v_pk_mul_f32 v[50:51], v[30:31], v[30:31]
	v_pk_fma_f32 v[44:45], v[44:45], s[18:19], v[46:47] op_sel_hi:[1,0,0] neg_lo:[1,0,0] neg_hi:[1,0,0]
	v_pk_fma_f32 v[50:51], v[50:51], s[18:19], v[46:47] op_sel_hi:[1,0,0] neg_lo:[1,0,0] neg_hi:[1,0,0]
	v_pk_fma_f32 v[32:33], v[32:33], s[18:19], v[46:47] op_sel_hi:[1,0,0] neg_lo:[1,0,0] neg_hi:[1,0,0]
	v_pk_fma_f32 v[46:47], v[48:49], s[18:19], v[46:47] op_sel_hi:[1,0,0] neg_lo:[1,0,0] neg_hi:[1,0,0]
	v_pk_mul_f32 v[44:45], v[28:29], v[44:45]
	v_pk_mul_f32 v[50:51], v[30:31], v[50:51]
	v_pk_mul_f32 v[32:33], v[42:43], v[32:33]
	v_pk_mul_f32 v[46:47], v[34:35], v[46:47]
	v_exp_f32_e32 v44, v44
	v_exp_f32_e32 v45, v45
	v_exp_f32_e32 v50, v50
	v_exp_f32_e32 v51, v51
	v_exp_f32_e32 v32, v32
	v_exp_f32_e32 v33, v33
	v_exp_f32_e32 v46, v46
	v_exp_f32_e32 v47, v47
	v_pk_add_f32 v[44:45], v[44:45], 1.0 op_sel_hi:[1,0]
	v_pk_add_f32 v[50:51], v[50:51], 1.0 op_sel_hi:[1,0]
	v_pk_add_f32 v[32:33], v[32:33], 1.0 op_sel_hi:[1,0]
	v_pk_add_f32 v[46:47], v[46:47], 1.0 op_sel_hi:[1,0]
	v_rcp_f32_e32 v44, v44
	v_rcp_f32_e32 v45, v45
	v_rcp_f32_e32 v50, v50
	v_rcp_f32_e32 v51, v51
	v_rcp_f32_e32 v32, v32
	v_rcp_f32_e32 v33, v33
	v_rcp_f32_e32 v46, v46
	v_rcp_f32_e32 v47, v47
	v_pk_mul_f32 v[28:29], v[28:29], v[44:45]
	v_pk_mul_f32 v[42:43], v[42:43], v[32:33]
	v_pk_mul_f32 v[30:31], v[30:31], v[50:51]
	v_pk_mul_f32 v[34:35], v[34:35], v[46:47]

.LBB0_184:
	s_nop 0
	s_and_b64 vcc, exec, s[0:1]
	s_waitcnt lgkmcnt(0)
	v_mov_b32_e32 v18, v249
	v_pk_mul_f32 v[20:21], v[12:13], v[18:19] op_sel_hi:[1,0]
	v_pk_mul_f32 v[10:11], v[10:11], v[18:19] op_sel_hi:[1,0]
	v_pk_mul_f32 v[16:17], v[16:17], v[18:19] op_sel_hi:[1,0]
	v_pk_mul_f32 v[12:13], v[14:15], v[18:19] op_sel_hi:[1,0]
	s_cbranch_vccnz .LBB0_186
	v_pk_mul_f32 v[14:15], v[20:21], v[20:21]
	v_pk_mul_f32 v[22:23], v[10:11], v[10:11]
	v_mov_b64_e32 v[24:25], s[42:43]
	v_pk_mul_f32 v[28:29], v[16:17], v[16:17]
	v_pk_mul_f32 v[30:31], v[12:13], v[12:13]
	v_pk_fma_f32 v[22:23], v[22:23], s[18:19], v[24:25] op_sel_hi:[1,0,0] neg_lo:[1,0,0] neg_hi:[1,0,0]
	v_pk_fma_f32 v[30:31], v[30:31], s[18:19], v[24:25] op_sel_hi:[1,0,0] neg_lo:[1,0,0] neg_hi:[1,0,0]
	v_pk_fma_f32 v[14:15], v[14:15], s[18:19], v[24:25] op_sel_hi:[1,0,0] neg_lo:[1,0,0] neg_hi:[1,0,0]
	v_pk_fma_f32 v[24:25], v[28:29], s[18:19], v[24:25] op_sel_hi:[1,0,0] neg_lo:[1,0,0] neg_hi:[1,0,0]
	v_pk_mul_f32 v[22:23], v[10:11], v[22:23]
	v_pk_mul_f32 v[30:31], v[12:13], v[30:31]
	v_pk_mul_f32 v[14:15], v[20:21], v[14:15]
	v_pk_mul_f32 v[24:25], v[16:17], v[24:25]
	v_exp_f32_e32 v22, v22
	v_exp_f32_e32 v23, v23
	v_exp_f32_e32 v30, v30
	v_exp_f32_e32 v31, v31
	v_exp_f32_e32 v14, v14
	v_exp_f32_e32 v15, v15
	v_exp_f32_e32 v24, v24
	v_exp_f32_e32 v25, v25
	v_pk_add_f32 v[22:23], v[22:23], 1.0 op_sel_hi:[1,0]
	v_pk_add_f32 v[30:31], v[30:31], 1.0 op_sel_hi:[1,0]
	v_pk_add_f32 v[14:15], v[14:15], 1.0 op_sel_hi:[1,0]
	v_pk_add_f32 v[24:25], v[24:25], 1.0 op_sel_hi:[1,0]
	v_rcp_f32_e32 v22, v22
	v_rcp_f32_e32 v23, v23
	v_rcp_f32_e32 v30, v30
	v_rcp_f32_e32 v31, v31
	v_rcp_f32_e32 v14, v14
	v_rcp_f32_e32 v15, v15
	v_rcp_f32_e32 v24, v24
	v_rcp_f32_e32 v25, v25
	v_pk_mul_f32 v[10:11], v[10:11], v[22:23]
	v_pk_mul_f32 v[20:21], v[20:21], v[14:15]
	v_pk_mul_f32 v[12:13], v[12:13], v[30:31]
	v_pk_mul_f32 v[16:17], v[16:17], v[24:25]
